# fused loop: static s_setprio 1 for waves 0-3 instead of 4-7, per-burst flips removed
# baseline (speedup 1.0000x reference)
; __global__ void __launch_bounds__(512, 2) mk_fwd(Args a) {
;     ...
;             for (;;) {
;                 if (tid == 0) *slot = (int)__hip_atomic_fetch_add(qc, 1u, __ATOMIC_RELAXED, __HIP_MEMORY_SCOPE_AGENT);
;                 __syncthreads();
;                 const int j = __builtin_amdgcn_readfirstlane(*slot);
;                 if (j >= 128) break;
;                 const int bb = 2 * x + (j & 1), qb = 63 - (j >> 1);
;                 _Pragma("unroll 1") for (int hf = 0; hf < 2; ++hf) { int tu = threadIdx.x; asm volatile("" : "+v"(tu)); indexer_unit(a5, lds, maskl + hf * 512, bb, 2 * qb + hf, wave, tu & 63); }
;                 { int tu = threadIdx.x; asm volatile("" : "+v"(tu)); dsa_unit32(a5, lds, maskl, bb, qb, tu, wave, tu & 63); }
.Ldq_prime_skip:
	s_mov_b64 exec, s[20:21]
	s_cmp_ge_u32 s85, 8
	s_cbranch_scc1 .Lprio_done
	s_setprio 1
